# group-barrier fast path polls with a returning atomic add of zero instead of an sc1 load; on top of v72
# baseline (speedup 1.0000x reference)
; __device__ __forceinline__ unsigned xb_ld(unsigned* p)              { return __hip_atomic_load(p, __ATOMIC_RELAXED, __HIP_MEMORY_SCOPE_AGENT); }
; __device__ __forceinline__ unsigned xb_add(unsigned* p, unsigned v) { return __hip_atomic_fetch_add(p, v, __ATOMIC_RELAXED, __HIP_MEMORY_SCOPE_AGENT); }
; #define XB_SPIN(cond, bar) do { unsigned _sp = 0; while (cond) { __builtin_amdgcn_s_sleep(1); \
;     if ((++_sp & 255u) == 0u) { if (xb_ld(&(bar)[XB_TMO])) break; if (_sp > XB_SPIN_CAP) { atomicAdd(&(bar)[XB_TMO], 1u); break; } } } } while (0)
; __device__ __forceinline__ void xcd_barrier(const XcdBarrier& b) {
;     ...
;             else XB_SPIN(xb_ld(&bar[XB_TOPGEN]) == tg, bar);
;             __builtin_amdgcn_fence(__ATOMIC_ACQUIRE, "agent");
;             xb_add(&bar[XB_XGEN(b.x)], 1u);
;             asm volatile("s_waitcnt vmcnt(0)" ::: "memory");
;         } else {
;             XB_SPIN(xb_ld(&bar[XB_XGEN(b.x)]) == gen, bar);
;             __builtin_amdgcn_fence(__ATOMIC_ACQUIRE, "agent");
;             asm volatile("s_waitcnt vmcnt(0)" ::: "memory");
;         }
.Lgb_spin_g1:
	global_atomic_add v3, v0, v175, s[38:39] sc0
	s_waitcnt vmcnt(0)
	v_sub_u32_e32 v3, v3, v2
	v_cmp_gt_i32_e32 vcc, 0, v3
	s_cbranch_vccz .Lgb_done_g1
	s_sleep 1
	s_add_i32 s40, s40, 1
	s_cmp_lt_u32 s40, 0x100000
	s_cbranch_scc1 .Lgb_spin_g1
